# dmaf: P5 K loop load segments issue their LDS-DMAs before the last ds_read group (pure reordering, +2 s_nop for the m0 hazard)
# baseline (speedup 1.0000x reference)
.LBB0_919:
	s_and_b64 vcc, exec, s[8:9]
	s_cbranch_vccnz .Lzx921
	s_add_u32 s40, s40, 0x80
	s_addc_u32 s41, s41, 0
	s_add_u32 s61, s42, 0x100
	s_addc_u32 s62, s43, 0
	s_mov_b32 s42, 0
	ds_read_b128 v[144:147], v153
	ds_read_b128 v[158:161], v153 offset:1024
	ds_read_b128 v[162:165], v153 offset:2048
	ds_read_b128 v[166:169], v153 offset:3072
	ds_read_b128 v[170:173], v154
	ds_read_b128 v[174:177], v154 offset:1024
	ds_read_b128 v[178:181], v154 offset:2048
	ds_read_b128 v[186:189], v154 offset:3072
	s_add_i32 s63, s42, 2
	s_add_u32 s64, s40, 0x80
	s_addc_u32 s43, s41, 0
	s_cmp_eq_u32 s50, s42
	s_cselect_b32 s42, s6, s64
	s_cselect_b32 s43, s7, s43
	s_cselect_b32 s65, s39, s62
	s_cselect_b32 s64, s38, s61
	s_mov_b32 m0, s53
	v_lshl_add_u64 v[148:149], s[40:41], 0, v[136:137]
	global_load_lds_dwordx4 v[148:149], off
	v_lshl_add_u64 v[148:149], s[40:41], 0, v[138:139]
	s_mov_b32 m0, s54
	s_nop 0
	global_load_lds_dwordx4 v[148:149], off
	ds_read_b128 v[190:193], v155
	ds_read_b128 v[194:197], v155 offset:1024
	ds_read_b128 v[198:201], v155 offset:2048
	ds_read_b128 v[202:205], v155 offset:3072
	ds_read_b128 v[206:209], v155 offset:4096
	ds_read_b128 v[210:213], v155 offset:5120
	ds_read_b128 v[214:217], v155 offset:6144
	ds_read_b128 v[224:227], v155 offset:7168
	s_waitcnt vmcnt(8)
	s_waitcnt lgkmcnt(0)
	s_barrier
	s_setprio 1
	s_waitcnt lgkmcnt(0)
	v_mfma_f32_16x16x32_bf16 v[120:123], v[144:147], v[190:193], 0
	v_mfma_f32_16x16x32_bf16 v[116:119], v[162:165], v[190:193], 0
	v_mfma_f32_16x16x32_bf16 v[108:111], v[144:147], v[198:201], 0
	v_mfma_f32_16x16x32_bf16 v[100:103], v[162:165], v[198:201], 0
	v_mfma_f32_16x16x32_bf16 v[92:95], v[144:147], v[206:209], 0
	v_mfma_f32_16x16x32_bf16 v[84:87], v[162:165], v[206:209], 0
	v_mfma_f32_16x16x32_bf16 v[76:79], v[144:147], v[214:217], 0
	v_mfma_f32_16x16x32_bf16 v[68:71], v[162:165], v[214:217], 0
	v_mfma_f32_16x16x32_bf16 v[120:123], v[158:161], v[194:197], v[120:123]
	v_mfma_f32_16x16x32_bf16 v[116:119], v[166:169], v[194:197], v[116:119]
	v_mfma_f32_16x16x32_bf16 v[108:111], v[158:161], v[202:205], v[108:111]
	v_mfma_f32_16x16x32_bf16 v[100:103], v[166:169], v[202:205], v[100:103]
	v_mfma_f32_16x16x32_bf16 v[92:95], v[158:161], v[210:213], v[92:95]
	v_mfma_f32_16x16x32_bf16 v[84:87], v[166:169], v[210:213], v[84:87]
	v_mfma_f32_16x16x32_bf16 v[76:79], v[158:161], v[224:227], v[76:79]
	v_mfma_f32_16x16x32_bf16 v[68:71], v[166:169], v[224:227], v[68:71]
	s_setprio 0
	s_setprio 1
	v_mfma_f32_16x16x32_bf16 v[124:127], v[170:173], v[190:193], 0
	v_mfma_f32_16x16x32_bf16 v[112:115], v[178:181], v[190:193], 0
	v_mfma_f32_16x16x32_bf16 v[104:107], v[170:173], v[198:201], 0
	v_mfma_f32_16x16x32_bf16 v[96:99], v[178:181], v[198:201], 0
	v_mfma_f32_16x16x32_bf16 v[88:91], v[170:173], v[206:209], 0
	v_mfma_f32_16x16x32_bf16 v[80:83], v[178:181], v[206:209], 0
	v_mfma_f32_16x16x32_bf16 v[72:75], v[170:173], v[214:217], 0
	v_mfma_f32_16x16x32_bf16 v[64:67], v[178:181], v[214:217], 0
	v_mfma_f32_16x16x32_bf16 v[124:127], v[174:177], v[194:197], v[124:127]
	v_mfma_f32_16x16x32_bf16 v[112:115], v[186:189], v[194:197], v[112:115]
	v_mfma_f32_16x16x32_bf16 v[104:107], v[174:177], v[202:205], v[104:107]
	v_mfma_f32_16x16x32_bf16 v[96:99], v[186:189], v[202:205], v[96:99]
	v_mfma_f32_16x16x32_bf16 v[88:91], v[174:177], v[210:213], v[88:91]
	v_mfma_f32_16x16x32_bf16 v[80:83], v[186:189], v[210:213], v[80:83]
	v_mfma_f32_16x16x32_bf16 v[72:75], v[174:177], v[224:227], v[72:75]
	v_mfma_f32_16x16x32_bf16 v[64:67], v[186:189], v[224:227], v[64:67]
	s_setprio 0
	s_barrier
	s_mov_b32 m0, s55
	v_lshl_add_u64 v[148:149], s[64:65], 0, v[132:133]
	v_lshl_add_u64 v[182:183], s[64:65], 0, v[128:129]
	s_add_u32 s64, s64, s16
	global_load_lds_dwordx4 v[148:149], off
	s_mov_b32 m0, s56
	s_addc_u32 s65, s65, s17
	s_add_i32 s66, s51, s31
	global_load_lds_dwordx4 v[182:183], off
	v_lshl_add_u64 v[228:229], s[64:65], 0, v[132:133]
	s_mov_b32 m0, s66
	v_lshl_add_u64 v[230:231], s[64:65], 0, v[128:129]
	global_load_lds_dwordx4 v[228:229], off
	s_add_i32 m0, s66, 0x2000
	v_lshl_add_u64 v[232:233], s[42:43], 0, v[134:135]
	global_load_lds_dwordx4 v[230:231], off
	v_lshl_add_u64 v[234:235], s[42:43], 0, v[130:131]
	ds_read_b128 v[190:193], v155 offset:16384
	ds_read_b128 v[194:197], v155 offset:17408
	ds_read_b128 v[198:201], v155 offset:18432
	ds_read_b128 v[202:205], v155 offset:19456
	ds_read_b128 v[206:209], v155 offset:20480
	ds_read_b128 v[210:213], v155 offset:21504
	ds_read_b128 v[214:217], v155 offset:22528
	ds_read_b128 v[224:227], v155 offset:23552
	s_waitcnt vmcnt(6)
	s_waitcnt lgkmcnt(0)
	s_barrier
	s_setprio 1
	s_waitcnt lgkmcnt(0)
	v_mfma_f32_16x16x32_bf16 v[60:63], v[144:147], v[190:193], 0
	v_mfma_f32_16x16x32_bf16 v[52:55], v[162:165], v[190:193], 0
	v_mfma_f32_16x16x32_bf16 v[44:47], v[144:147], v[198:201], 0
	v_mfma_f32_16x16x32_bf16 v[36:39], v[162:165], v[198:201], 0
	v_mfma_f32_16x16x32_bf16 v[28:31], v[144:147], v[206:209], 0
	v_mfma_f32_16x16x32_bf16 v[20:23], v[162:165], v[206:209], 0
	v_mfma_f32_16x16x32_bf16 v[12:15], v[144:147], v[214:217], 0
	v_mfma_f32_16x16x32_bf16 v[4:7], v[162:165], v[214:217], 0
	v_mfma_f32_16x16x32_bf16 v[60:63], v[158:161], v[194:197], v[60:63]
	v_mfma_f32_16x16x32_bf16 v[52:55], v[166:169], v[194:197], v[52:55]
	v_mfma_f32_16x16x32_bf16 v[44:47], v[158:161], v[202:205], v[44:47]
	v_mfma_f32_16x16x32_bf16 v[36:39], v[166:169], v[202:205], v[36:39]
	v_mfma_f32_16x16x32_bf16 v[28:31], v[158:161], v[210:213], v[28:31]
	v_mfma_f32_16x16x32_bf16 v[20:23], v[166:169], v[210:213], v[20:23]
	v_mfma_f32_16x16x32_bf16 v[12:15], v[158:161], v[224:227], v[12:15]
	v_mfma_f32_16x16x32_bf16 v[4:7], v[166:169], v[224:227], v[4:7]
	s_setprio 0
	s_setprio 1
	v_mfma_f32_16x16x32_bf16 v[56:59], v[170:173], v[190:193], 0
	v_mfma_f32_16x16x32_bf16 v[48:51], v[178:181], v[190:193], 0
	v_mfma_f32_16x16x32_bf16 v[40:43], v[170:173], v[198:201], 0
	v_mfma_f32_16x16x32_bf16 v[32:35], v[178:181], v[198:201], 0
	v_mfma_f32_16x16x32_bf16 v[24:27], v[170:173], v[206:209], 0
	v_mfma_f32_16x16x32_bf16 v[16:19], v[178:181], v[206:209], 0
	v_mfma_f32_16x16x32_bf16 v[8:11], v[170:173], v[214:217], 0
	v_mfma_f32_16x16x32_bf16 v[0:3], v[178:181], v[214:217], 0
	v_mfma_f32_16x16x32_bf16 v[56:59], v[174:177], v[194:197], v[56:59]
	v_mfma_f32_16x16x32_bf16 v[48:51], v[186:189], v[194:197], v[48:51]
	v_mfma_f32_16x16x32_bf16 v[40:43], v[174:177], v[202:205], v[40:43]
	v_mfma_f32_16x16x32_bf16 v[32:35], v[186:189], v[202:205], v[32:35]
	v_mfma_f32_16x16x32_bf16 v[24:27], v[174:177], v[210:213], v[24:27]
	v_mfma_f32_16x16x32_bf16 v[16:19], v[186:189], v[210:213], v[16:19]
	v_mfma_f32_16x16x32_bf16 v[8:11], v[174:177], v[224:227], v[8:11]
	v_mfma_f32_16x16x32_bf16 v[0:3], v[186:189], v[224:227], v[0:3]
	s_setprio 0
	s_barrier
	s_add_i32 s64, 0, 0x18000
	v_add_u32_e32 v157, s64, v151
	s_add_i32 s65, 0, 0x1c000
	ds_read_b128 v[144:147], v157
	ds_read_b128 v[158:161], v157 offset:1024
	ds_read_b128 v[162:165], v157 offset:2048
	ds_read_b128 v[166:169], v157 offset:3072
	v_add_u32_e32 v157, s65, v151
	ds_read_b128 v[170:173], v157
	ds_read_b128 v[174:177], v157 offset:1024
	ds_read_b128 v[178:181], v157 offset:2048
	ds_read_b128 v[186:189], v157 offset:3072
	s_add_u32 s42, s42, s16
	s_addc_u32 s43, s43, s17
	s_mov_b32 m0, s28
	s_nop 0
	global_load_lds_dwordx4 v[232:233], off
	s_mov_b32 m0, s33
	s_nop 0
	global_load_lds_dwordx4 v[234:235], off
	s_mov_b32 m0, s44
	v_lshl_add_u64 v[236:237], s[42:43], 0, v[134:135]
	global_load_lds_dwordx4 v[236:237], off
	v_lshl_add_u64 v[236:237], s[42:43], 0, v[130:131]
	s_mov_b32 m0, s45
	s_nop 0
	global_load_lds_dwordx4 v[236:237], off
	ds_read_b128 v[190:193], v155 offset:32768
	ds_read_b128 v[194:197], v155 offset:33792
	ds_read_b128 v[198:201], v155 offset:34816
	ds_read_b128 v[202:205], v155 offset:35840
	ds_read_b128 v[206:209], v155 offset:36864
	ds_read_b128 v[210:213], v155 offset:37888
	ds_read_b128 v[214:217], v155 offset:38912
	ds_read_b128 v[224:227], v155 offset:39936
	s_waitcnt vmcnt(8)
	s_waitcnt lgkmcnt(0)
	s_barrier
	s_setprio 1
	s_waitcnt lgkmcnt(0)
	v_mfma_f32_16x16x32_bf16 v[120:123], v[144:147], v[190:193], v[120:123]
	v_mfma_f32_16x16x32_bf16 v[116:119], v[162:165], v[190:193], v[116:119]
	v_mfma_f32_16x16x32_bf16 v[108:111], v[144:147], v[198:201], v[108:111]
	v_mfma_f32_16x16x32_bf16 v[100:103], v[162:165], v[198:201], v[100:103]
	v_mfma_f32_16x16x32_bf16 v[92:95], v[144:147], v[206:209], v[92:95]
	v_mfma_f32_16x16x32_bf16 v[84:87], v[162:165], v[206:209], v[84:87]
	v_mfma_f32_16x16x32_bf16 v[76:79], v[144:147], v[214:217], v[76:79]
	v_mfma_f32_16x16x32_bf16 v[68:71], v[162:165], v[214:217], v[68:71]
	v_mfma_f32_16x16x32_bf16 v[120:123], v[158:161], v[194:197], v[120:123]
	v_mfma_f32_16x16x32_bf16 v[116:119], v[166:169], v[194:197], v[116:119]
	v_mfma_f32_16x16x32_bf16 v[108:111], v[158:161], v[202:205], v[108:111]
	v_mfma_f32_16x16x32_bf16 v[100:103], v[166:169], v[202:205], v[100:103]
	v_mfma_f32_16x16x32_bf16 v[92:95], v[158:161], v[210:213], v[92:95]
	v_mfma_f32_16x16x32_bf16 v[84:87], v[166:169], v[210:213], v[84:87]
	v_mfma_f32_16x16x32_bf16 v[76:79], v[158:161], v[224:227], v[76:79]
	v_mfma_f32_16x16x32_bf16 v[68:71], v[166:169], v[224:227], v[68:71]
	s_setprio 0
	s_setprio 1
	v_mfma_f32_16x16x32_bf16 v[124:127], v[170:173], v[190:193], v[124:127]
	v_mfma_f32_16x16x32_bf16 v[112:115], v[178:181], v[190:193], v[112:115]
	v_mfma_f32_16x16x32_bf16 v[104:107], v[170:173], v[198:201], v[104:107]
	v_mfma_f32_16x16x32_bf16 v[96:99], v[178:181], v[198:201], v[96:99]
	v_mfma_f32_16x16x32_bf16 v[88:91], v[170:173], v[206:209], v[88:91]
	v_mfma_f32_16x16x32_bf16 v[80:83], v[178:181], v[206:209], v[80:83]
	v_mfma_f32_16x16x32_bf16 v[72:75], v[170:173], v[214:217], v[72:75]
	v_mfma_f32_16x16x32_bf16 v[64:67], v[178:181], v[214:217], v[64:67]
	v_mfma_f32_16x16x32_bf16 v[124:127], v[174:177], v[194:197], v[124:127]
	v_mfma_f32_16x16x32_bf16 v[112:115], v[186:189], v[194:197], v[112:115]
	v_mfma_f32_16x16x32_bf16 v[104:107], v[174:177], v[202:205], v[104:107]
	v_mfma_f32_16x16x32_bf16 v[96:99], v[186:189], v[202:205], v[96:99]
	v_mfma_f32_16x16x32_bf16 v[88:91], v[174:177], v[210:213], v[88:91]
	v_mfma_f32_16x16x32_bf16 v[80:83], v[186:189], v[210:213], v[80:83]
	v_mfma_f32_16x16x32_bf16 v[72:75], v[174:177], v[224:227], v[72:75]
	v_mfma_f32_16x16x32_bf16 v[64:67], v[186:189], v[224:227], v[64:67]
	s_setprio 0
	s_barrier
	s_add_i32 s42, s64, s31
	v_lshl_add_u64 v[148:149], v[148:149], 0, s[36:37]
	s_mov_b32 m0, s42
	s_nop 0
	global_load_lds_dwordx4 v[148:149], off
	v_lshl_add_u64 v[148:149], v[182:183], 0, s[36:37]
	s_add_i32 m0, s42, 0x2000
	s_add_i32 s42, s65, s31
	global_load_lds_dwordx4 v[148:149], off
	v_lshl_add_u64 v[148:149], v[228:229], 0, s[36:37]
	s_mov_b32 m0, s42
	s_nop 0
	global_load_lds_dwordx4 v[148:149], off
	v_lshl_add_u64 v[148:149], v[230:231], 0, s[36:37]
	s_add_i32 m0, s42, 0x2000
	s_nop 0
	global_load_lds_dwordx4 v[148:149], off
	ds_read_b128 v[190:193], v155 offset:49152
	ds_read_b128 v[194:197], v155 offset:50176
	ds_read_b128 v[198:201], v155 offset:51200
	ds_read_b128 v[202:205], v155 offset:52224
	ds_read_b128 v[206:209], v155 offset:53248
	ds_read_b128 v[210:213], v155 offset:54272
	ds_read_b128 v[214:217], v155 offset:55296
	ds_read_b128 v[224:227], v155 offset:56320
	s_waitcnt vmcnt(6)
	s_waitcnt lgkmcnt(0)
	s_barrier
	s_setprio 1
	s_waitcnt lgkmcnt(0)
	v_mfma_f32_16x16x32_bf16 v[60:63], v[144:147], v[190:193], v[60:63]
	v_mfma_f32_16x16x32_bf16 v[52:55], v[162:165], v[190:193], v[52:55]
	v_mfma_f32_16x16x32_bf16 v[44:47], v[144:147], v[198:201], v[44:47]
	v_mfma_f32_16x16x32_bf16 v[36:39], v[162:165], v[198:201], v[36:39]
	v_mfma_f32_16x16x32_bf16 v[28:31], v[144:147], v[206:209], v[28:31]
	v_mfma_f32_16x16x32_bf16 v[20:23], v[162:165], v[206:209], v[20:23]
	v_mfma_f32_16x16x32_bf16 v[12:15], v[144:147], v[214:217], v[12:15]
	v_mfma_f32_16x16x32_bf16 v[4:7], v[162:165], v[214:217], v[4:7]
	v_mfma_f32_16x16x32_bf16 v[60:63], v[158:161], v[194:197], v[60:63]
	v_mfma_f32_16x16x32_bf16 v[52:55], v[166:169], v[194:197], v[52:55]
	v_mfma_f32_16x16x32_bf16 v[44:47], v[158:161], v[202:205], v[44:47]
	v_mfma_f32_16x16x32_bf16 v[36:39], v[166:169], v[202:205], v[36:39]
	v_mfma_f32_16x16x32_bf16 v[28:31], v[158:161], v[210:213], v[28:31]
	v_mfma_f32_16x16x32_bf16 v[20:23], v[166:169], v[210:213], v[20:23]
	v_mfma_f32_16x16x32_bf16 v[12:15], v[158:161], v[224:227], v[12:15]
	v_mfma_f32_16x16x32_bf16 v[4:7], v[166:169], v[224:227], v[4:7]
	s_setprio 0
	s_setprio 1
	v_mfma_f32_16x16x32_bf16 v[56:59], v[170:173], v[190:193], v[56:59]
	v_mfma_f32_16x16x32_bf16 v[48:51], v[178:181], v[190:193], v[48:51]
	v_mfma_f32_16x16x32_bf16 v[40:43], v[170:173], v[198:201], v[40:43]
	v_mfma_f32_16x16x32_bf16 v[32:35], v[178:181], v[198:201], v[32:35]
	v_mfma_f32_16x16x32_bf16 v[24:27], v[170:173], v[206:209], v[24:27]
	v_mfma_f32_16x16x32_bf16 v[16:19], v[178:181], v[206:209], v[16:19]
	v_mfma_f32_16x16x32_bf16 v[8:11], v[170:173], v[214:217], v[8:11]
	v_mfma_f32_16x16x32_bf16 v[0:3], v[178:181], v[214:217], v[0:3]
	v_mfma_f32_16x16x32_bf16 v[56:59], v[174:177], v[194:197], v[56:59]
	v_mfma_f32_16x16x32_bf16 v[48:51], v[186:189], v[194:197], v[48:51]
	v_mfma_f32_16x16x32_bf16 v[40:43], v[174:177], v[202:205], v[40:43]
	v_mfma_f32_16x16x32_bf16 v[32:35], v[186:189], v[202:205], v[32:35]
	v_mfma_f32_16x16x32_bf16 v[24:27], v[174:177], v[210:213], v[24:27]
	v_mfma_f32_16x16x32_bf16 v[16:19], v[186:189], v[210:213], v[16:19]
	v_mfma_f32_16x16x32_bf16 v[8:11], v[174:177], v[224:227], v[8:11]
	v_mfma_f32_16x16x32_bf16 v[0:3], v[186:189], v[224:227], v[0:3]
	s_setprio 0
	s_barrier
	s_add_u32 s40, s40, 0x100
	s_addc_u32 s41, s41, 0
	s_add_u32 s61, s61, 0x100
	s_addc_u32 s62, s62, 0
	s_cmp_ge_i32 s63, s49
	s_mov_b32 s42, s63
	s_cbranch_scc1 .LBB0_922
.LBB0_921:
	ds_read_b128 v[144:147], v153
	ds_read_b128 v[158:161], v153 offset:1024
	ds_read_b128 v[162:165], v153 offset:2048
	ds_read_b128 v[166:169], v153 offset:3072
	ds_read_b128 v[170:173], v154
	ds_read_b128 v[174:177], v154 offset:1024
	ds_read_b128 v[178:181], v154 offset:2048
	ds_read_b128 v[186:189], v154 offset:3072
	s_add_i32 s63, s42, 2
	s_add_u32 s64, s40, 0x80
	s_addc_u32 s43, s41, 0
	s_cmp_eq_u32 s50, s42
	s_cselect_b32 s42, s6, s64
	s_cselect_b32 s43, s7, s43
	s_cselect_b32 s65, s39, s62
	s_cselect_b32 s64, s38, s61
	v_lshl_add_u64 v[148:149], v[232:233], 0, s[36:37]
	s_mov_b32 m0, s47
	s_nop 0
	global_load_lds_dwordx4 v[148:149], off
	v_lshl_add_u64 v[148:149], v[234:235], 0, s[36:37]
	s_mov_b32 m0, s48
	s_nop 0
	global_load_lds_dwordx4 v[148:149], off
	s_mov_b32 m0, s53
	v_lshl_add_u64 v[148:149], s[40:41], 0, v[136:137]
	global_load_lds_dwordx4 v[148:149], off
	v_lshl_add_u64 v[148:149], s[40:41], 0, v[138:139]
	s_mov_b32 m0, s54
	s_nop 0
	global_load_lds_dwordx4 v[148:149], off
	ds_read_b128 v[190:193], v155
	ds_read_b128 v[194:197], v155 offset:1024
	ds_read_b128 v[198:201], v155 offset:2048
	ds_read_b128 v[202:205], v155 offset:3072
	ds_read_b128 v[206:209], v155 offset:4096
	ds_read_b128 v[210:213], v155 offset:5120
	ds_read_b128 v[214:217], v155 offset:6144
	ds_read_b128 v[224:227], v155 offset:7168
	s_waitcnt vmcnt(8)
	s_waitcnt lgkmcnt(0)
	s_barrier
	s_setprio 1
	s_waitcnt lgkmcnt(0)
	v_mfma_f32_16x16x32_bf16 v[120:123], v[144:147], v[190:193], v[120:123]
	v_mfma_f32_16x16x32_bf16 v[116:119], v[162:165], v[190:193], v[116:119]
	v_mfma_f32_16x16x32_bf16 v[108:111], v[144:147], v[198:201], v[108:111]
	v_mfma_f32_16x16x32_bf16 v[100:103], v[162:165], v[198:201], v[100:103]
	v_mfma_f32_16x16x32_bf16 v[92:95], v[144:147], v[206:209], v[92:95]
	v_mfma_f32_16x16x32_bf16 v[84:87], v[162:165], v[206:209], v[84:87]
	v_mfma_f32_16x16x32_bf16 v[76:79], v[144:147], v[214:217], v[76:79]
	v_mfma_f32_16x16x32_bf16 v[68:71], v[162:165], v[214:217], v[68:71]
	v_mfma_f32_16x16x32_bf16 v[120:123], v[158:161], v[194:197], v[120:123]
	v_mfma_f32_16x16x32_bf16 v[116:119], v[166:169], v[194:197], v[116:119]
	v_mfma_f32_16x16x32_bf16 v[108:111], v[158:161], v[202:205], v[108:111]
	v_mfma_f32_16x16x32_bf16 v[100:103], v[166:169], v[202:205], v[100:103]
	v_mfma_f32_16x16x32_bf16 v[92:95], v[158:161], v[210:213], v[92:95]
	v_mfma_f32_16x16x32_bf16 v[84:87], v[166:169], v[210:213], v[84:87]
	v_mfma_f32_16x16x32_bf16 v[76:79], v[158:161], v[224:227], v[76:79]
	v_mfma_f32_16x16x32_bf16 v[68:71], v[166:169], v[224:227], v[68:71]
	s_setprio 0
	s_setprio 1
	v_mfma_f32_16x16x32_bf16 v[124:127], v[170:173], v[190:193], v[124:127]
	v_mfma_f32_16x16x32_bf16 v[112:115], v[178:181], v[190:193], v[112:115]
	v_mfma_f32_16x16x32_bf16 v[104:107], v[170:173], v[198:201], v[104:107]
	v_mfma_f32_16x16x32_bf16 v[96:99], v[178:181], v[198:201], v[96:99]
	v_mfma_f32_16x16x32_bf16 v[88:91], v[170:173], v[206:209], v[88:91]
	v_mfma_f32_16x16x32_bf16 v[80:83], v[178:181], v[206:209], v[80:83]
	v_mfma_f32_16x16x32_bf16 v[72:75], v[170:173], v[214:217], v[72:75]
	v_mfma_f32_16x16x32_bf16 v[64:67], v[178:181], v[214:217], v[64:67]
	v_mfma_f32_16x16x32_bf16 v[124:127], v[174:177], v[194:197], v[124:127]
	v_mfma_f32_16x16x32_bf16 v[112:115], v[186:189], v[194:197], v[112:115]
	v_mfma_f32_16x16x32_bf16 v[104:107], v[174:177], v[202:205], v[104:107]
	v_mfma_f32_16x16x32_bf16 v[96:99], v[186:189], v[202:205], v[96:99]
	v_mfma_f32_16x16x32_bf16 v[88:91], v[174:177], v[210:213], v[88:91]
	v_mfma_f32_16x16x32_bf16 v[80:83], v[186:189], v[210:213], v[80:83]
	v_mfma_f32_16x16x32_bf16 v[72:75], v[174:177], v[224:227], v[72:75]
	v_mfma_f32_16x16x32_bf16 v[64:67], v[186:189], v[224:227], v[64:67]
	s_setprio 0
	s_barrier
	s_mov_b32 m0, s55
	v_lshl_add_u64 v[148:149], s[64:65], 0, v[132:133]
	v_lshl_add_u64 v[182:183], s[64:65], 0, v[128:129]
	s_add_u32 s64, s64, s16
	global_load_lds_dwordx4 v[148:149], off
	s_mov_b32 m0, s56
	s_addc_u32 s65, s65, s17
	s_add_i32 s66, s51, s31
	global_load_lds_dwordx4 v[182:183], off
	v_lshl_add_u64 v[228:229], s[64:65], 0, v[132:133]
	s_mov_b32 m0, s66
	v_lshl_add_u64 v[230:231], s[64:65], 0, v[128:129]
	global_load_lds_dwordx4 v[228:229], off
	s_add_i32 m0, s66, 0x2000
	v_lshl_add_u64 v[232:233], s[42:43], 0, v[134:135]
	global_load_lds_dwordx4 v[230:231], off
	v_lshl_add_u64 v[234:235], s[42:43], 0, v[130:131]
	ds_read_b128 v[190:193], v155 offset:16384
	ds_read_b128 v[194:197], v155 offset:17408
	ds_read_b128 v[198:201], v155 offset:18432
	ds_read_b128 v[202:205], v155 offset:19456
	ds_read_b128 v[206:209], v155 offset:20480
	ds_read_b128 v[210:213], v155 offset:21504
	ds_read_b128 v[214:217], v155 offset:22528
	ds_read_b128 v[224:227], v155 offset:23552
	s_waitcnt vmcnt(6)
	s_waitcnt lgkmcnt(0)
	s_barrier
	s_setprio 1
	s_waitcnt lgkmcnt(0)
	v_mfma_f32_16x16x32_bf16 v[60:63], v[144:147], v[190:193], v[60:63]
	v_mfma_f32_16x16x32_bf16 v[52:55], v[162:165], v[190:193], v[52:55]
	v_mfma_f32_16x16x32_bf16 v[44:47], v[144:147], v[198:201], v[44:47]
	v_mfma_f32_16x16x32_bf16 v[36:39], v[162:165], v[198:201], v[36:39]
	v_mfma_f32_16x16x32_bf16 v[28:31], v[144:147], v[206:209], v[28:31]
	v_mfma_f32_16x16x32_bf16 v[20:23], v[162:165], v[206:209], v[20:23]
	v_mfma_f32_16x16x32_bf16 v[12:15], v[144:147], v[214:217], v[12:15]
	v_mfma_f32_16x16x32_bf16 v[4:7], v[162:165], v[214:217], v[4:7]
	v_mfma_f32_16x16x32_bf16 v[60:63], v[158:161], v[194:197], v[60:63]
	v_mfma_f32_16x16x32_bf16 v[52:55], v[166:169], v[194:197], v[52:55]
	v_mfma_f32_16x16x32_bf16 v[44:47], v[158:161], v[202:205], v[44:47]
	v_mfma_f32_16x16x32_bf16 v[36:39], v[166:169], v[202:205], v[36:39]
	v_mfma_f32_16x16x32_bf16 v[28:31], v[158:161], v[210:213], v[28:31]
	v_mfma_f32_16x16x32_bf16 v[20:23], v[166:169], v[210:213], v[20:23]
	v_mfma_f32_16x16x32_bf16 v[12:15], v[158:161], v[224:227], v[12:15]
	v_mfma_f32_16x16x32_bf16 v[4:7], v[166:169], v[224:227], v[4:7]
	s_setprio 0
	s_setprio 1
	v_mfma_f32_16x16x32_bf16 v[56:59], v[170:173], v[190:193], v[56:59]
	v_mfma_f32_16x16x32_bf16 v[48:51], v[178:181], v[190:193], v[48:51]
	v_mfma_f32_16x16x32_bf16 v[40:43], v[170:173], v[198:201], v[40:43]
	v_mfma_f32_16x16x32_bf16 v[32:35], v[178:181], v[198:201], v[32:35]
	v_mfma_f32_16x16x32_bf16 v[24:27], v[170:173], v[206:209], v[24:27]
	v_mfma_f32_16x16x32_bf16 v[16:19], v[178:181], v[206:209], v[16:19]
	v_mfma_f32_16x16x32_bf16 v[8:11], v[170:173], v[214:217], v[8:11]
	v_mfma_f32_16x16x32_bf16 v[0:3], v[178:181], v[214:217], v[0:3]
	v_mfma_f32_16x16x32_bf16 v[56:59], v[174:177], v[194:197], v[56:59]
	v_mfma_f32_16x16x32_bf16 v[48:51], v[186:189], v[194:197], v[48:51]
	v_mfma_f32_16x16x32_bf16 v[40:43], v[174:177], v[202:205], v[40:43]
	v_mfma_f32_16x16x32_bf16 v[32:35], v[186:189], v[202:205], v[32:35]
	v_mfma_f32_16x16x32_bf16 v[24:27], v[174:177], v[210:213], v[24:27]
	v_mfma_f32_16x16x32_bf16 v[16:19], v[186:189], v[210:213], v[16:19]
	v_mfma_f32_16x16x32_bf16 v[8:11], v[174:177], v[224:227], v[8:11]
	v_mfma_f32_16x16x32_bf16 v[0:3], v[186:189], v[224:227], v[0:3]
	s_setprio 0
	s_barrier
	s_add_i32 s64, 0, 0x18000
	v_add_u32_e32 v157, s64, v151
	s_add_i32 s65, 0, 0x1c000
	ds_read_b128 v[144:147], v157
	ds_read_b128 v[158:161], v157 offset:1024
	ds_read_b128 v[162:165], v157 offset:2048
	ds_read_b128 v[166:169], v157 offset:3072
	v_add_u32_e32 v157, s65, v151
	ds_read_b128 v[170:173], v157
	ds_read_b128 v[174:177], v157 offset:1024
	ds_read_b128 v[178:181], v157 offset:2048
	ds_read_b128 v[186:189], v157 offset:3072
	s_add_u32 s42, s42, s16
	s_addc_u32 s43, s43, s17
	s_mov_b32 m0, s28
	s_nop 0
	global_load_lds_dwordx4 v[232:233], off
	s_mov_b32 m0, s33
	s_nop 0
	global_load_lds_dwordx4 v[234:235], off
	s_mov_b32 m0, s44
	v_lshl_add_u64 v[236:237], s[42:43], 0, v[134:135]
	global_load_lds_dwordx4 v[236:237], off
	v_lshl_add_u64 v[236:237], s[42:43], 0, v[130:131]
	s_mov_b32 m0, s45
	s_nop 0
	global_load_lds_dwordx4 v[236:237], off
	ds_read_b128 v[190:193], v155 offset:32768
	ds_read_b128 v[194:197], v155 offset:33792
	ds_read_b128 v[198:201], v155 offset:34816
	ds_read_b128 v[202:205], v155 offset:35840
	ds_read_b128 v[206:209], v155 offset:36864
	ds_read_b128 v[210:213], v155 offset:37888
	ds_read_b128 v[214:217], v155 offset:38912
	ds_read_b128 v[224:227], v155 offset:39936
	s_waitcnt vmcnt(8)
	s_waitcnt lgkmcnt(0)
	s_barrier
	s_setprio 1
	s_waitcnt lgkmcnt(0)
	v_mfma_f32_16x16x32_bf16 v[120:123], v[144:147], v[190:193], v[120:123]
	v_mfma_f32_16x16x32_bf16 v[116:119], v[162:165], v[190:193], v[116:119]
	v_mfma_f32_16x16x32_bf16 v[108:111], v[144:147], v[198:201], v[108:111]
	v_mfma_f32_16x16x32_bf16 v[100:103], v[162:165], v[198:201], v[100:103]
	v_mfma_f32_16x16x32_bf16 v[92:95], v[144:147], v[206:209], v[92:95]
	v_mfma_f32_16x16x32_bf16 v[84:87], v[162:165], v[206:209], v[84:87]
	v_mfma_f32_16x16x32_bf16 v[76:79], v[144:147], v[214:217], v[76:79]
	v_mfma_f32_16x16x32_bf16 v[68:71], v[162:165], v[214:217], v[68:71]
	v_mfma_f32_16x16x32_bf16 v[120:123], v[158:161], v[194:197], v[120:123]
	v_mfma_f32_16x16x32_bf16 v[116:119], v[166:169], v[194:197], v[116:119]
	v_mfma_f32_16x16x32_bf16 v[108:111], v[158:161], v[202:205], v[108:111]
	v_mfma_f32_16x16x32_bf16 v[100:103], v[166:169], v[202:205], v[100:103]
	v_mfma_f32_16x16x32_bf16 v[92:95], v[158:161], v[210:213], v[92:95]
	v_mfma_f32_16x16x32_bf16 v[84:87], v[166:169], v[210:213], v[84:87]
	v_mfma_f32_16x16x32_bf16 v[76:79], v[158:161], v[224:227], v[76:79]
	v_mfma_f32_16x16x32_bf16 v[68:71], v[166:169], v[224:227], v[68:71]
	s_setprio 0
	s_setprio 1
	v_mfma_f32_16x16x32_bf16 v[124:127], v[170:173], v[190:193], v[124:127]
	v_mfma_f32_16x16x32_bf16 v[112:115], v[178:181], v[190:193], v[112:115]
	v_mfma_f32_16x16x32_bf16 v[104:107], v[170:173], v[198:201], v[104:107]
	v_mfma_f32_16x16x32_bf16 v[96:99], v[178:181], v[198:201], v[96:99]
	v_mfma_f32_16x16x32_bf16 v[88:91], v[170:173], v[206:209], v[88:91]
	v_mfma_f32_16x16x32_bf16 v[80:83], v[178:181], v[206:209], v[80:83]
	v_mfma_f32_16x16x32_bf16 v[72:75], v[170:173], v[214:217], v[72:75]
	v_mfma_f32_16x16x32_bf16 v[64:67], v[178:181], v[214:217], v[64:67]
	v_mfma_f32_16x16x32_bf16 v[124:127], v[174:177], v[194:197], v[124:127]
	v_mfma_f32_16x16x32_bf16 v[112:115], v[186:189], v[194:197], v[112:115]
	v_mfma_f32_16x16x32_bf16 v[104:107], v[174:177], v[202:205], v[104:107]
	v_mfma_f32_16x16x32_bf16 v[96:99], v[186:189], v[202:205], v[96:99]
	v_mfma_f32_16x16x32_bf16 v[88:91], v[174:177], v[210:213], v[88:91]
	v_mfma_f32_16x16x32_bf16 v[80:83], v[186:189], v[210:213], v[80:83]
	v_mfma_f32_16x16x32_bf16 v[72:75], v[174:177], v[224:227], v[72:75]
	v_mfma_f32_16x16x32_bf16 v[64:67], v[186:189], v[224:227], v[64:67]
	s_setprio 0
	s_barrier
	s_add_i32 s42, s64, s31
	v_lshl_add_u64 v[148:149], v[148:149], 0, s[36:37]
	s_mov_b32 m0, s42
	s_nop 0
	global_load_lds_dwordx4 v[148:149], off
	v_lshl_add_u64 v[148:149], v[182:183], 0, s[36:37]
	s_add_i32 m0, s42, 0x2000
	s_add_i32 s42, s65, s31
	global_load_lds_dwordx4 v[148:149], off
	v_lshl_add_u64 v[148:149], v[228:229], 0, s[36:37]
	s_mov_b32 m0, s42
	s_nop 0
	global_load_lds_dwordx4 v[148:149], off
	v_lshl_add_u64 v[148:149], v[230:231], 0, s[36:37]
	s_add_i32 m0, s42, 0x2000
	s_nop 0
	global_load_lds_dwordx4 v[148:149], off
	ds_read_b128 v[190:193], v155 offset:49152
	ds_read_b128 v[194:197], v155 offset:50176
	ds_read_b128 v[198:201], v155 offset:51200
	ds_read_b128 v[202:205], v155 offset:52224
	ds_read_b128 v[206:209], v155 offset:53248
	ds_read_b128 v[210:213], v155 offset:54272
	ds_read_b128 v[214:217], v155 offset:55296
	ds_read_b128 v[224:227], v155 offset:56320
	s_waitcnt vmcnt(6)
	s_waitcnt lgkmcnt(0)
	s_barrier
	s_setprio 1
	s_waitcnt lgkmcnt(0)
	v_mfma_f32_16x16x32_bf16 v[60:63], v[144:147], v[190:193], v[60:63]
	v_mfma_f32_16x16x32_bf16 v[52:55], v[162:165], v[190:193], v[52:55]
	v_mfma_f32_16x16x32_bf16 v[44:47], v[144:147], v[198:201], v[44:47]
	v_mfma_f32_16x16x32_bf16 v[36:39], v[162:165], v[198:201], v[36:39]
	v_mfma_f32_16x16x32_bf16 v[28:31], v[144:147], v[206:209], v[28:31]
	v_mfma_f32_16x16x32_bf16 v[20:23], v[162:165], v[206:209], v[20:23]
	v_mfma_f32_16x16x32_bf16 v[12:15], v[144:147], v[214:217], v[12:15]
	v_mfma_f32_16x16x32_bf16 v[4:7], v[162:165], v[214:217], v[4:7]
	v_mfma_f32_16x16x32_bf16 v[60:63], v[158:161], v[194:197], v[60:63]
	v_mfma_f32_16x16x32_bf16 v[52:55], v[166:169], v[194:197], v[52:55]
	v_mfma_f32_16x16x32_bf16 v[44:47], v[158:161], v[202:205], v[44:47]
	v_mfma_f32_16x16x32_bf16 v[36:39], v[166:169], v[202:205], v[36:39]
	v_mfma_f32_16x16x32_bf16 v[28:31], v[158:161], v[210:213], v[28:31]
	v_mfma_f32_16x16x32_bf16 v[20:23], v[166:169], v[210:213], v[20:23]
	v_mfma_f32_16x16x32_bf16 v[12:15], v[158:161], v[224:227], v[12:15]
	v_mfma_f32_16x16x32_bf16 v[4:7], v[166:169], v[224:227], v[4:7]
	s_setprio 0
	s_setprio 1
	v_mfma_f32_16x16x32_bf16 v[56:59], v[170:173], v[190:193], v[56:59]
	v_mfma_f32_16x16x32_bf16 v[48:51], v[178:181], v[190:193], v[48:51]
	v_mfma_f32_16x16x32_bf16 v[40:43], v[170:173], v[198:201], v[40:43]
	v_mfma_f32_16x16x32_bf16 v[32:35], v[178:181], v[198:201], v[32:35]
	v_mfma_f32_16x16x32_bf16 v[24:27], v[170:173], v[206:209], v[24:27]
	v_mfma_f32_16x16x32_bf16 v[16:19], v[178:181], v[206:209], v[16:19]
	v_mfma_f32_16x16x32_bf16 v[8:11], v[170:173], v[214:217], v[8:11]
	v_mfma_f32_16x16x32_bf16 v[0:3], v[178:181], v[214:217], v[0:3]
	v_mfma_f32_16x16x32_bf16 v[56:59], v[174:177], v[194:197], v[56:59]
	v_mfma_f32_16x16x32_bf16 v[48:51], v[186:189], v[194:197], v[48:51]
	v_mfma_f32_16x16x32_bf16 v[40:43], v[174:177], v[202:205], v[40:43]
	v_mfma_f32_16x16x32_bf16 v[32:35], v[186:189], v[202:205], v[32:35]
	v_mfma_f32_16x16x32_bf16 v[24:27], v[174:177], v[210:213], v[24:27]
	v_mfma_f32_16x16x32_bf16 v[16:19], v[186:189], v[210:213], v[16:19]
	v_mfma_f32_16x16x32_bf16 v[8:11], v[174:177], v[224:227], v[8:11]
	v_mfma_f32_16x16x32_bf16 v[0:3], v[186:189], v[224:227], v[0:3]
	s_setprio 0
	s_barrier
	s_add_u32 s40, s40, 0x100
	s_addc_u32 s41, s41, 0
	s_add_u32 s61, s61, 0x100
	s_addc_u32 s62, s62, 0
	s_cmp_ge_i32 s63, s49
	s_mov_b32 s42, s63
	s_cbranch_scc0 .LBB0_921
	s_branch .LBB0_922
